# rmsnorm row prefetch with exact counted wait (9 stores younger)
# speedup vs baseline: 1.0050x; 1.0050x over previous
; #define LAS __attribute__((address_space(3)))
; DI void norm_row(const float* xrow, const LAS f32x4* wfl, const float* fbias, bf16_t* orow, float* logf_b  , int s, int lane) {
;     ...
;     for (int j = 0; j < 8; ++j) { v[j] = ((const f32x4*)xrow)[lane + 64 * j]; ss += (v[j][0] * v[j][0] + v[j][1] * v[j][1]) + (v[j][2] * v[j][2] + v[j][3] * v[j][3]); }
; __global__ void __launch_bounds__(512, 2) mega_fwd(Args a) {
;     ...
;             for (int m = gw; m < MT; m += NGW) {
;                 const int b = m / S, s = m % S;
;                 norm_row(src + (size_t)m * DM, (const LAS f32x4*)lds, ap->fb + l * 8, XB + (size_t)m * DM, LOGF + (size_t)b * 8 * S, s, lane);
.LBB0_53:
	s_ashr_i32 s1, s0, 31
	s_lshl_b64 s[2:3], s[0:1], 13
	s_lshl_b64 s[2:3], s[0:1], 12
	s_nop 0
	ds_read_b128 v[58:61], v50
	ds_read_b128 v[62:65], v50 offset:1024
	ds_read_b128 v[66:69], v50 offset:2048
	ds_read_b128 v[70:73], v50 offset:3072
	ds_read_b128 v[38:41], v50 offset:4096
	ds_read_b128 v[34:37], v50 offset:5120
	ds_read_b128 v[74:77], v50 offset:6144
	ds_read_b128 v[78:81], v50 offset:7168
	ds_read_b128 v[82:85], v50 offset:8192
	ds_read_b128 v[86:89], v50 offset:9216
	ds_read_b128 v[90:93], v50 offset:10240
	ds_read_b128 v[94:97], v50 offset:11264
	s_nop 0
	s_waitcnt vmcnt(9)
	v_mov_b32_e32 v2, v200
	v_mov_b32_e32 v3, v201
	v_mov_b32_e32 v4, v202
	v_mov_b32_e32 v5, v203
	v_mov_b32_e32 v6, v204
	v_mov_b32_e32 v7, v205
	v_mov_b32_e32 v8, v206
	v_mov_b32_e32 v9, v207
	v_mov_b32_e32 v10, v208
	v_mov_b32_e32 v11, v209
	v_mov_b32_e32 v12, v210
	v_mov_b32_e32 v13, v211
	v_mov_b32_e32 v14, v212
	v_mov_b32_e32 v15, v213
	v_mov_b32_e32 v16, v214
	v_mov_b32_e32 v17, v215
	v_mov_b32_e32 v18, v216
	v_mov_b32_e32 v19, v217
	v_mov_b32_e32 v20, v218
	v_mov_b32_e32 v21, v219
	v_mov_b32_e32 v22, v220
	v_mov_b32_e32 v23, v221
	v_mov_b32_e32 v24, v222
	v_mov_b32_e32 v25, v223
	v_mov_b32_e32 v26, v224
	v_mov_b32_e32 v27, v225
	v_mov_b32_e32 v28, v226
	v_mov_b32_e32 v29, v227
	v_mov_b32_e32 v30, v228
	v_mov_b32_e32 v31, v229
	v_mov_b32_e32 v32, v230
	v_mov_b32_e32 v33, v231
	s_add_i32 s22, s0, s24
	s_cmpk_gt_i32 s22, 0x3fff
	s_cbranch_scc1 .Lnorm_nopf
	s_ashr_i32 s23, s22, 31
	s_lshl_b64 s[22:23], s[22:23], 13
	v_lshl_add_u64 v[234:235], v[42:43], 0, s[22:23]
	s_mov_b64 s[22:23], 0x1000
	v_lshl_add_u64 v[236:237], v[234:235], 0, s[22:23]
	global_load_dwordx4 v[216:219], v[234:235], off
	global_load_dwordx4 v[212:215], v[234:235], off offset:2048
	global_load_dwordx4 v[208:211], v[236:237], off
	global_load_dwordx4 v[204:207], v[236:237], off offset:1024
	global_load_dwordx4 v[200:203], v[236:237], off offset:3072
	global_load_dwordx4 v[220:223], v[234:235], off offset:1024
	global_load_dwordx4 v[228:231], v[234:235], off offset:3072
	global_load_dwordx4 v[224:227], v[236:237], off offset:2048
